# attention steady state: reference max fixed after tile 0, re-referenced by an exact power of two only when the running sum exceeds 2^24 (one check per iteration) - removes both per-tile max chains, sw
# speedup vs baseline: 1.0053x; 1.0024x over previous
.Latt_noload:
	ds_read_b128 v[66:69], v0 offset:0
	ds_read_b128 v[70:73], v0 offset:6656
	ds_read_b128 v[74:77], v0 offset:32
	ds_read_b128 v[78:81], v0 offset:6688
	ds_read_b128 v[212:215], v0 offset:64
	ds_read_b128 v[240:243], v0 offset:6720
	ds_read_b128 v[244:247], v0 offset:96
	s_waitcnt lgkmcnt(6)
	v_mfma_f32_32x32x16_bf16 v[114:129], v[66:69], v[154:157], v[82:97]
	ds_read_b128 v[248:251], v0 offset:6752
	s_waitcnt lgkmcnt(6)
	v_mfma_f32_32x32x16_bf16 v[98:113], v[70:73], v[154:157], v[82:97]
	ds_read_b128 v[66:69], v0 offset:128
	s_waitcnt lgkmcnt(6)
	v_mfma_f32_32x32x16_bf16 v[114:129], v[74:77], v[158:161], v[114:129]
	ds_read_b128 v[70:73], v0 offset:6784
	s_waitcnt lgkmcnt(6)
	v_mfma_f32_32x32x16_bf16 v[98:113], v[78:81], v[158:161], v[98:113]
	ds_read_b128 v[74:77], v0 offset:160
	s_waitcnt lgkmcnt(6)
	v_mfma_f32_32x32x16_bf16 v[114:129], v[212:215], v[162:165], v[114:129]
	ds_read_b128 v[78:81], v0 offset:6816
	s_waitcnt lgkmcnt(6)
	v_mfma_f32_32x32x16_bf16 v[98:113], v[240:243], v[162:165], v[98:113]
	ds_read_b128 v[212:215], v0 offset:13312
	s_waitcnt lgkmcnt(6)
	v_mfma_f32_32x32x16_bf16 v[114:129], v[244:247], v[166:169], v[114:129]
	ds_read_b128 v[240:243], v0 offset:19968
	s_waitcnt lgkmcnt(6)
	v_mfma_f32_32x32x16_bf16 v[98:113], v[248:251], v[166:169], v[98:113]
	ds_read_b128 v[244:247], v0 offset:13344
	s_waitcnt lgkmcnt(6)
	v_mfma_f32_32x32x16_bf16 v[114:129], v[66:69], v[170:173], v[114:129]
	ds_read_b128 v[248:251], v0 offset:20000
	s_waitcnt lgkmcnt(6)
	v_mfma_f32_32x32x16_bf16 v[98:113], v[70:73], v[170:173], v[98:113]
	ds_read_b128 v[66:69], v0 offset:13376
	s_waitcnt lgkmcnt(6)
	v_mfma_f32_32x32x16_bf16 v[114:129], v[74:77], v[174:177], v[114:129]
	ds_read_b128 v[70:73], v0 offset:20032
	s_waitcnt lgkmcnt(6)
	v_mfma_f32_32x32x16_bf16 v[98:113], v[78:81], v[174:177], v[98:113]
	ds_read_b128 v[74:77], v0 offset:13408
	s_waitcnt lgkmcnt(6)
	v_mfma_f32_32x32x16_bf16 v[2:17], v[212:215], v[154:157], v[82:97]
	ds_read_b128 v[78:81], v0 offset:20064
	s_waitcnt lgkmcnt(6)
	v_mfma_f32_32x32x16_bf16 v[18:33], v[240:243], v[154:157], v[82:97]
	ds_read_b128 v[212:215], v0 offset:13440
	s_waitcnt lgkmcnt(6)
	v_mfma_f32_32x32x16_bf16 v[2:17], v[244:247], v[158:161], v[2:17]
	ds_read_b128 v[240:243], v0 offset:20096
	s_waitcnt lgkmcnt(6)
	v_mfma_f32_32x32x16_bf16 v[18:33], v[248:251], v[158:161], v[18:33]
	ds_read_b128 v[244:247], v0 offset:13472
	s_waitcnt lgkmcnt(6)
	v_mfma_f32_32x32x16_bf16 v[2:17], v[66:69], v[162:165], v[2:17]
	ds_read_b128 v[248:251], v0 offset:20128
	s_waitcnt lgkmcnt(6)
	v_mfma_f32_32x32x16_bf16 v[18:33], v[70:73], v[162:165], v[18:33]
	ds_read_b64_tr_b16 v[216:217], v185 offset:53248
	ds_read_b64_tr_b16 v[218:219], v185 offset:53760
	s_waitcnt lgkmcnt(7)
	v_mfma_f32_32x32x16_bf16 v[2:17], v[74:77], v[166:169], v[2:17]
	ds_read_b64_tr_b16 v[220:221], v185 offset:57344
	ds_read_b64_tr_b16 v[222:223], v185 offset:57856
	s_waitcnt lgkmcnt(8)
	v_mfma_f32_32x32x16_bf16 v[18:33], v[78:81], v[166:169], v[18:33]
	ds_read_b64_tr_b16 v[224:225], v185 offset:54272
	ds_read_b64_tr_b16 v[226:227], v185 offset:54784
	s_waitcnt lgkmcnt(9)
	v_mfma_f32_32x32x16_bf16 v[2:17], v[212:215], v[170:173], v[2:17]
	ds_read_b64_tr_b16 v[228:229], v185 offset:58368
	ds_read_b64_tr_b16 v[230:231], v185 offset:58880
	s_waitcnt lgkmcnt(10)
	v_mfma_f32_32x32x16_bf16 v[18:33], v[240:243], v[170:173], v[18:33]
	ds_read_b64_tr_b16 v[232:233], v185 offset:55296
	ds_read_b64_tr_b16 v[234:235], v185 offset:55808
	s_waitcnt lgkmcnt(11)
	v_mfma_f32_32x32x16_bf16 v[2:17], v[244:247], v[174:177], v[2:17]
	ds_read_b64_tr_b16 v[236:237], v185 offset:59392
	ds_read_b64_tr_b16 v[238:239], v185 offset:59904
	s_waitcnt lgkmcnt(12)
	v_mfma_f32_32x32x16_bf16 v[18:33], v[248:251], v[174:177], v[18:33]
	v_exp_f32_e32 v114, v114
	v_exp_f32_e32 v115, v115
	v_exp_f32_e32 v116, v116
	v_exp_f32_e32 v117, v117
	v_exp_f32_e32 v118, v118
	v_exp_f32_e32 v119, v119
	v_exp_f32_e32 v120, v120
	v_exp_f32_e32 v121, v121
	s_nop 0
	v_cvt_pk_bf16_f32 v66, v114, v115
	v_cvt_pk_bf16_f32 v67, v116, v117
	v_cvt_pk_bf16_f32 v68, v118, v119
	v_cvt_pk_bf16_f32 v69, v120, v121
	v_add_f32_e32 v178, v114, v115
	v_add_f32_e32 v179, v116, v117
	v_add_f32_e32 v180, v118, v119
	v_add_f32_e32 v181, v120, v121
	v_add_f32_e32 v178, v178, v179
	v_add_f32_e32 v180, v180, v181
	v_add_f32_e32 v178, v178, v180
	v_add_f32_e32 v210, v210, v178
	ds_read_b64_tr_b16 v[240:241], v185 offset:56320
	ds_read_b64_tr_b16 v[242:243], v185 offset:56832
	ds_read_b64_tr_b16 v[244:245], v185 offset:60416
	s_waitcnt lgkmcnt(11)
	ds_read_b64_tr_b16 v[246:247], v185 offset:60928
	ds_read_b64_tr_b16 v[114:115], v184 offset:53248
	ds_read_b64_tr_b16 v[116:117], v184 offset:53760
	ds_read_b64_tr_b16 v[118:119], v184 offset:57344
	s_waitcnt lgkmcnt(11)
	ds_read_b64_tr_b16 v[120:121], v184 offset:57856
	v_exp_f32_e32 v122, v122
	v_exp_f32_e32 v123, v123
	v_exp_f32_e32 v124, v124
	v_mfma_f32_32x32x16_bf16 v[34:49], v[66:69], v[216:219], v[34:49]
	v_exp_f32_e32 v125, v125
	v_exp_f32_e32 v126, v126
	v_exp_f32_e32 v127, v127
	v_exp_f32_e32 v128, v128
	v_exp_f32_e32 v129, v129
	s_nop 0
	v_cvt_pk_bf16_f32 v70, v122, v123
	v_cvt_pk_bf16_f32 v71, v124, v125
	v_mfma_f32_32x32x16_bf16 v[50:65], v[66:69], v[220:223], v[50:65]
	v_cvt_pk_bf16_f32 v72, v126, v127
	v_cvt_pk_bf16_f32 v73, v128, v129
	v_add_f32_e32 v178, v122, v123
	v_add_f32_e32 v179, v124, v125
	v_add_f32_e32 v180, v126, v127
	v_add_f32_e32 v181, v128, v129
	v_add_f32_e32 v178, v178, v179
	v_add_f32_e32 v180, v180, v181
	v_add_f32_e32 v178, v178, v180
	v_add_f32_e32 v210, v210, v178
	ds_read_b64_tr_b16 v[122:123], v184 offset:54272
	ds_read_b64_tr_b16 v[124:125], v184 offset:54784
	ds_read_b64_tr_b16 v[126:127], v184 offset:58368
	s_waitcnt lgkmcnt(11)
; #define AT_LOAD(X, t) do { const size_t adv_ = (size_t)(t) * 64; sk##X = *(const u32x4*)(gk + adv_ * 1024); sv##X = *(const u32x4*)(gv + adv_ * 1024); if (rth) sr##X = *(const u32x4*)(gr + adv_ * 32); } while (0)
; #define AT_STORE(X, slot) do { *(LAS u32x4*)(lds + A_K0 + (slot) * AK_BYTES + lk) = sk##X; *(LAS u32x4*)(lds + A_V0 + (slot) * AV_BYTES + lv) = sv##X; if (rth) *(LAS u32x4*)(lds + A_K0 + (slot) * AK_BYTES + lr) = sr##X; } while (0)
; __device__ __forceinline__ void attn_unit(LAS char* lds, const bf16_t* Qp, const bf16_t* KVp, const bf16_t* KRp, int ntiles, bf16_t* Yp, bool dry) {
;     ...
;     for (int t = 0; t < ntiles; t += 2) {
;         const int sb0 = (t & 2);
;         const bool more = (t + 2 < ntiles);
;         f32x16 pa0 = {}, pa1 = {}, pb0 = {}, pb1 = {};
;         AT_QK(sb0, pa0, pa1);
;         AT_QK(sb0 + 1, pb0, pb1);
;         if (t == 0) AT_SMPV(sb0, true, pa0, pa1); else AT_SMPV(sb0, false, pa0, pa1);
;         __builtin_amdgcn_sched_barrier(0);
;         if (more) { AT_LOAD(A, t + 2); AT_LOAD(B, t + 3); }
;         AT_SMPV(sb0 + 1, false, pb0, pb1);
;         if (more) { AT_STORE(A, sb0 ^ 2); AT_STORE(B, (sb0 ^ 2) + 1); }
	ds_read_b64_tr_b16 v[128:129], v184 offset:58880
	v_exp_f32_e32 v98, v98
	v_exp_f32_e32 v99, v99
	v_exp_f32_e32 v100, v100
	v_mfma_f32_32x32x16_bf16 v[34:49], v[70:73], v[224:227], v[34:49]
	v_exp_f32_e32 v101, v101
	v_exp_f32_e32 v102, v102
	v_exp_f32_e32 v103, v103
	v_exp_f32_e32 v104, v104
	v_exp_f32_e32 v105, v105
	s_nop 0
	v_cvt_pk_bf16_f32 v74, v98, v99
	v_cvt_pk_bf16_f32 v75, v100, v101
	v_mfma_f32_32x32x16_bf16 v[50:65], v[70:73], v[228:231], v[50:65]
	v_cvt_pk_bf16_f32 v76, v102, v103
	v_cvt_pk_bf16_f32 v77, v104, v105
	v_add_f32_e32 v178, v98, v99
	v_add_f32_e32 v179, v100, v101
	v_add_f32_e32 v180, v102, v103
	v_add_f32_e32 v181, v104, v105
	v_add_f32_e32 v178, v178, v179
	v_add_f32_e32 v180, v180, v181
	v_add_f32_e32 v178, v178, v180
	v_add_f32_e32 v210, v210, v178
	ds_read_b64_tr_b16 v[98:99], v184 offset:55296
	ds_read_b64_tr_b16 v[100:101], v184 offset:55808
	ds_read_b64_tr_b16 v[102:103], v184 offset:59392
	s_waitcnt lgkmcnt(11)
	ds_read_b64_tr_b16 v[104:105], v184 offset:59904
	v_exp_f32_e32 v106, v106
	v_exp_f32_e32 v107, v107
	v_exp_f32_e32 v108, v108
	v_mfma_f32_32x32x16_bf16 v[34:49], v[74:77], v[232:235], v[34:49]
	v_exp_f32_e32 v109, v109
	v_exp_f32_e32 v110, v110
	v_exp_f32_e32 v111, v111
	v_exp_f32_e32 v112, v112
	v_exp_f32_e32 v113, v113
	s_nop 0
	v_cvt_pk_bf16_f32 v78, v106, v107
	v_cvt_pk_bf16_f32 v79, v108, v109
	v_mfma_f32_32x32x16_bf16 v[50:65], v[74:77], v[236:239], v[50:65]
	v_cvt_pk_bf16_f32 v80, v110, v111
	v_cvt_pk_bf16_f32 v81, v112, v113
	v_add_f32_e32 v178, v106, v107
	v_add_f32_e32 v179, v108, v109
	v_add_f32_e32 v180, v110, v111
	v_add_f32_e32 v181, v112, v113
	v_add_f32_e32 v178, v178, v179
	v_add_f32_e32 v180, v180, v181
	v_add_f32_e32 v178, v178, v180
	v_add_f32_e32 v210, v210, v178
	ds_read_b64_tr_b16 v[106:107], v184 offset:56320
	ds_read_b64_tr_b16 v[108:109], v184 offset:56832
	ds_read_b64_tr_b16 v[110:111], v184 offset:60416
	s_waitcnt lgkmcnt(11)
	ds_read_b64_tr_b16 v[112:113], v184 offset:60928
	v_exp_f32_e32 v2, v2
	v_exp_f32_e32 v3, v3
	v_exp_f32_e32 v4, v4
	v_mfma_f32_32x32x16_bf16 v[34:49], v[78:81], v[240:243], v[34:49]
	v_exp_f32_e32 v5, v5
	v_exp_f32_e32 v6, v6
	v_exp_f32_e32 v7, v7
	v_exp_f32_e32 v8, v8
	v_exp_f32_e32 v9, v9
	s_nop 0
	v_cvt_pk_bf16_f32 v66, v2, v3
	v_cvt_pk_bf16_f32 v67, v4, v5
	v_mfma_f32_32x32x16_bf16 v[50:65], v[78:81], v[244:247], v[50:65]
	v_cvt_pk_bf16_f32 v68, v6, v7
	v_cvt_pk_bf16_f32 v69, v8, v9
	v_add_f32_e32 v178, v2, v3
	v_add_f32_e32 v179, v4, v5
	v_add_f32_e32 v180, v6, v7
	v_add_f32_e32 v181, v8, v9
	v_add_f32_e32 v178, v178, v179
	v_add_f32_e32 v180, v180, v181
	v_add_f32_e32 v178, v178, v180
	v_add_f32_e32 v210, v210, v178
	v_exp_f32_e32 v10, v10
	v_exp_f32_e32 v11, v11
	v_exp_f32_e32 v12, v12
	v_mfma_f32_32x32x16_bf16 v[34:49], v[66:69], v[114:117], v[34:49]
	v_exp_f32_e32 v13, v13
	v_exp_f32_e32 v14, v14
	v_exp_f32_e32 v15, v15
	v_exp_f32_e32 v16, v16
	v_exp_f32_e32 v17, v17
	s_nop 0
	v_cvt_pk_bf16_f32 v70, v10, v11
	v_cvt_pk_bf16_f32 v71, v12, v13
	v_mfma_f32_32x32x16_bf16 v[50:65], v[66:69], v[118:121], v[50:65]
	v_cvt_pk_bf16_f32 v72, v14, v15
	v_cvt_pk_bf16_f32 v73, v16, v17
	v_add_f32_e32 v178, v10, v11
	v_add_f32_e32 v179, v12, v13
	v_add_f32_e32 v180, v14, v15
	v_add_f32_e32 v181, v16, v17
	v_add_f32_e32 v178, v178, v179
	v_add_f32_e32 v180, v180, v181
	v_add_f32_e32 v178, v178, v180
	v_add_f32_e32 v210, v210, v178
	v_exp_f32_e32 v18, v18
	v_exp_f32_e32 v19, v19
	v_exp_f32_e32 v20, v20
	s_waitcnt lgkmcnt(10)
	v_mfma_f32_32x32x16_bf16 v[34:49], v[70:73], v[122:125], v[34:49]
	v_exp_f32_e32 v21, v21
	v_exp_f32_e32 v22, v22
	v_exp_f32_e32 v23, v23
	v_exp_f32_e32 v24, v24
	v_exp_f32_e32 v25, v25
	s_nop 0
	v_cvt_pk_bf16_f32 v74, v18, v19
	v_cvt_pk_bf16_f32 v75, v20, v21
	s_waitcnt lgkmcnt(8)
	v_mfma_f32_32x32x16_bf16 v[50:65], v[70:73], v[126:129], v[50:65]
	v_cvt_pk_bf16_f32 v76, v22, v23
	v_cvt_pk_bf16_f32 v77, v24, v25
	v_add_f32_e32 v178, v18, v19
	v_add_f32_e32 v179, v20, v21
	v_add_f32_e32 v180, v22, v23
	v_add_f32_e32 v181, v24, v25
	v_add_f32_e32 v178, v178, v179
	v_add_f32_e32 v180, v180, v181
	v_add_f32_e32 v178, v178, v180
	v_add_f32_e32 v210, v210, v178
	v_exp_f32_e32 v26, v26
	v_exp_f32_e32 v27, v27
	v_exp_f32_e32 v28, v28
	s_waitcnt lgkmcnt(6)
	v_mfma_f32_32x32x16_bf16 v[34:49], v[74:77], v[98:101], v[34:49]
	v_exp_f32_e32 v29, v29
	v_exp_f32_e32 v30, v30
	v_exp_f32_e32 v31, v31
	v_exp_f32_e32 v32, v32
	v_exp_f32_e32 v33, v33
	s_nop 0
	v_cvt_pk_bf16_f32 v78, v26, v27
	v_cvt_pk_bf16_f32 v79, v28, v29
	s_waitcnt lgkmcnt(4)
	v_mfma_f32_32x32x16_bf16 v[50:65], v[74:77], v[102:105], v[50:65]
	v_cvt_pk_bf16_f32 v80, v30, v31
	v_cvt_pk_bf16_f32 v81, v32, v33
	v_add_f32_e32 v178, v26, v27
	v_add_f32_e32 v179, v28, v29
	v_add_f32_e32 v180, v30, v31
	v_add_f32_e32 v181, v32, v33
	v_add_f32_e32 v178, v178, v179
	v_add_f32_e32 v180, v180, v181
	v_add_f32_e32 v178, v178, v180
	v_add_f32_e32 v210, v210, v178
	s_waitcnt lgkmcnt(2)
	v_mfma_f32_32x32x16_bf16 v[34:49], v[78:81], v[106:109], v[34:49]
	s_waitcnt lgkmcnt(0)
	v_mfma_f32_32x32x16_bf16 v[50:65], v[78:81], v[110:113], v[50:65]
	v_cmp_lt_f32_e32 vcc, 0x4b800000, v210
	s_cbranch_vccnz .Latt_rs
.Latt_rsback:
	s_cmp_gt_u32 s35, 33
	s_cbranch_scc1 .Latt_latch
	s_xor_b32 s14, s42, 2
	s_mul_i32 s17, s14, 0x3400
	s_add_i32 s16, s17, 0
	v_add_u32_e32 v2, s16, v190
	s_waitcnt vmcnt(3)
	ds_write_b128 v2, v[130:133]
	v_lshl_add_u32 v2, s14, 13, v201
	s_waitcnt vmcnt(2)
	ds_write_b128 v2, v[134:137] offset:53248
	s_and_saveexec_b64 s[14:15], s[0:1]
	s_xor_b64 s[14:15], exec, s[14:15]
	s_cbranch_execz .Latt_st1
	v_add_u32_e32 v3, s17, v200
	s_waitcnt vmcnt(1)
	ds_write_b128 v3, v[146:149] offset:13312
	s_waitcnt vmcnt(0)
	ds_write_b128 v2, v[150:153] offset:61440

.Latt_rs:
	s_nop 15
	v_frexp_exp_i32_f32_e32 v211, v210
	v_mov_b32_e32 v179, v211
	s_nop 1
	v_permlane32_swap_b32_e32 v179, v211
	v_max_i32_e32 v211, v211, v179
	v_max_i32_e32 v211, 0, v211
	v_sub_u32_e32 v179, 0, v211
	v_cvt_f32_i32_e32 v178, v211
	v_ldexp_f32 v180, 1.0, v179
	s_and_saveexec_b64 s[2:3], s[40:41]
	ds_write_b32 v207, v180
	s_or_b64 exec, exec, s[2:3]
	s_waitcnt lgkmcnt(0)
	v_add_f32_e32 v189, v189, v178
	v_ldexp_f32 v210, v210, v179
	ds_read_b128 v[66:69], v199 offset:0
	ds_read_b128 v[70:73], v199 offset:32
	ds_read_b128 v[74:77], v199 offset:64
	ds_read_b128 v[78:81], v199 offset:96
	v_sub_f32_e32 v82, v82, v178
	v_sub_f32_e32 v83, v83, v178
	v_sub_f32_e32 v84, v84, v178
	v_sub_f32_e32 v85, v85, v178
	v_sub_f32_e32 v86, v86, v178
	v_sub_f32_e32 v87, v87, v178
	v_sub_f32_e32 v88, v88, v178
	v_sub_f32_e32 v89, v89, v178
	v_sub_f32_e32 v90, v90, v178
	v_sub_f32_e32 v91, v91, v178
	v_sub_f32_e32 v92, v92, v178
	v_sub_f32_e32 v93, v93, v178
	v_sub_f32_e32 v94, v94, v178
	v_sub_f32_e32 v95, v95, v178
	v_sub_f32_e32 v96, v96, v178
	v_sub_f32_e32 v97, v97, v178
	s_waitcnt lgkmcnt(0)
	v_mul_f32_e32 v34, v34, v66
	v_mul_f32_e32 v50, v50, v66
	v_mul_f32_e32 v35, v35, v67
	v_mul_f32_e32 v51, v51, v67
	v_mul_f32_e32 v36, v36, v68
	v_mul_f32_e32 v52, v52, v68
	v_mul_f32_e32 v37, v37, v69
	v_mul_f32_e32 v53, v53, v69
	v_mul_f32_e32 v38, v38, v70
	v_mul_f32_e32 v54, v54, v70
	v_mul_f32_e32 v39, v39, v71
	v_mul_f32_e32 v55, v55, v71
	v_mul_f32_e32 v40, v40, v72
	v_mul_f32_e32 v56, v56, v72
	v_mul_f32_e32 v41, v41, v73
	v_mul_f32_e32 v57, v57, v73
	v_mul_f32_e32 v42, v42, v74
	v_mul_f32_e32 v58, v58, v74
	v_mul_f32_e32 v43, v43, v75
	v_mul_f32_e32 v59, v59, v75
	v_mul_f32_e32 v44, v44, v76
	v_mul_f32_e32 v60, v60, v76
	v_mul_f32_e32 v45, v45, v77
	v_mul_f32_e32 v61, v61, v77
	v_mul_f32_e32 v46, v46, v78
	v_mul_f32_e32 v62, v62, v78
	v_mul_f32_e32 v47, v47, v79
	v_mul_f32_e32 v63, v63, v79
	v_mul_f32_e32 v48, v48, v80
	v_mul_f32_e32 v64, v64, v80
	v_mul_f32_e32 v49, v49, v81
	v_mul_f32_e32 v65, v65, v81
	s_nop 1
	s_branch .Latt_rsback
